# grid barrier 4 removed: attention items count per M-tile (write-through outputs), each merge-GEMM tile waits only for the 8 items of its own M-tile
# speedup vs baseline: 1.0058x; 1.0058x over previous
.Lp3_setup:
	s_add_u32 s4, s38, 0x6000000
	s_addc_u32 s5, s39, 0
	s_mov_b32 s43, 0
	s_add_u32 s40, s38, 0x6500000
	s_mov_b32 s3, s43
	s_addc_u32 s41, s39, 0
	s_lshl_b64 s[6:7], s[2:3], 3
	s_add_u32 s3, s0, s6
	s_addc_u32 s67, s1, s7
	s_cmpk_lg_i32 s33, 0x100
	s_cselect_b64 s[44:45], -1, 0
	s_add_u32 s46, s38, 0x2080000
	s_addc_u32 s47, s39, 0
	s_add_u32 s48, s38, 0x57c0000
	s_addc_u32 s49, s39, 0
	s_add_u32 s50, s38, 0x67a8000
	s_addc_u32 s51, s39, 0
	s_add_u32 s52, s38, 0x77e8000
	s_movk_i32 s68, 0x100
	s_addc_u32 s53, s39, 0
	v_mov_b32_e32 v1, 0
	s_movk_i32 s69, 0xa00
	s_movk_i32 s70, 0xa0
	s_movk_i32 s71, 0x140
	s_mov_b64 s[54:55], 0x2800
	s_movk_i32 s72, 0x2000
	s_mov_b64 s[56:57], 0x100
	s_movk_i32 s73, 0x800
	s_mov_b64 s[58:59], 0x5100
	s_mov_b64 s[60:61], 0x5000
	s_movk_i32 s74, 0x1000
	s_movk_i32 s75, 0x3000
	v_mov_b32_e32 v164, 0xf149f2ca
	v_mbcnt_hi_u32_b32 v197, -1, v214
	s_mov_b32 s42, s43
	s_mov_b32 s96, 0
	s_bfe_u32 s10, s83, 0x10001
	s_lshl_b32 s10, s10, 8
	s_addk_i32 s10, 0x3700
	s_and_saveexec_b64 s[6:7], s[80:81]
	s_cbranch_execz .Lq_init_done
	v_mov_b32_e32 v2, s10
	v_mov_b32_e32 v3, 1
	global_atomic_add v215, v2, v3, s[78:79] sc0
	s_waitcnt vmcnt(0)
	v_mov_b32_e32 v2, 0xf000
	ds_write_b32 v2, v215
	s_waitcnt lgkmcnt(0)

.Lq_done:
	s_lshr_b32 s97, s14, 3
	s_lshl_b32 s97, s97, 2
	s_addk_i32 s97, 0x3c00



.LBB0_485:
	s_or_b64 exec, exec, s[12:13]
	v_lshrrev_b32_e32 v8, 3, v165
	v_and_b32_e32 v8, 2, v8
	v_bfe_u32 v9, v165, 1, 1
	v_bfe_u32 v7, v165, 2, 2
	v_or_b32_e32 v10, v8, v9
	v_lshlrev_b32_e32 v166, 2, v4
	v_lshlrev_b32_e32 v11, 3, v165
	v_and_b32_e32 v11, 8, v11
	v_or_b32_e32 v13, v166, v7
	v_bitop3_b32 v8, v8, v4, v9 bitop3:0x36
	v_bitop3_b32 v10, v4, v10, 2 bitop3:0x36
	v_lshlrev_b32_e32 v3, 2, v165
	v_lshlrev_b32_e32 v12, 6, v7
	v_lshlrev_b32_e32 v13, 8, v13
	v_lshlrev_b32_e32 v8, 4, v8
	v_lshl_or_b32 v10, v10, 4, v11
	s_waitcnt vmcnt(0)
	v_or3_b32 v8, v13, v8, v11
	v_xor_b32_e32 v9, 64, v12
	v_xor_b32_e32 v14, 0x80, v12
	v_xor_b32_e32 v15, 0xc0, v12
	v_or3_b32 v10, v13, v10, s73
	v_and_b32_e32 v3, 12, v3
	v_and_b32_e32 v167, 31, v165
	v_or_b32_e32 v155, v8, v12
	v_or_b32_e32 v168, v8, v9
	v_or_b32_e32 v169, v8, v14
	v_or_b32_e32 v170, v8, v15
	v_or_b32_e32 v8, 2, v4
	v_add_u32_e32 v172, v10, v9
	v_or_b32_e32 v9, v3, v7
	v_bitop3_b32 v3, v3, v4, v7 bitop3:0x36
	v_lshlrev_b32_e32 v184, 8, v167
	v_add_u32_e32 v171, v10, v12
	v_add_u32_e32 v173, v10, v14
	v_add_u32_e32 v174, v10, v15
	v_lshlrev_b32_e32 v176, 6, v167
	v_lshlrev_b32_e32 v189, 4, v3
	s_cmp_eq_u32 s15, 1
	v_xor_b32_e32 v188, v8, v9
	v_bitop3_b32 v187, v4, v9, 4 bitop3:0x36
	v_bitop3_b32 v186, v4, v9, 6 bitop3:0x36
	v_bitop3_b32 v185, v4, v9, 8 bitop3:0x36
	v_bitop3_b32 v182, v4, v9, 10 bitop3:0x36
	v_bitop3_b32 v180, v4, v9, 12 bitop3:0x36
	v_bitop3_b32 v179, v4, v9, 14 bitop3:0x36
	v_xor_b32_e32 v178, v4, v7
	v_xor_b32_e32 v177, v8, v7
	s_waitcnt vmcnt(0) lgkmcnt(0)
	s_barrier
	s_cmp_eq_u32 s96, 0
	s_cbranch_scc1 .Lrel_none_item
	s_and_saveexec_b64 s[18:19], s[80:81]
	s_cbranch_execz .Lrel_done_item
	v_mov_b32_e32 v2, s96
	v_mov_b32_e32 v3, 1
	global_atomic_add v2, v3, s[78:79]
.Lrel_done_item:
	s_or_b64 exec, exec, s[18:19]
	s_mov_b32 s96, 0
.Lrel_none_item:
	v_add_u32_e32 v190, v184, v189
	v_lshl_add_u32 v191, v188, 4, v184
	v_lshl_add_u32 v192, v187, 4, v184
	v_lshl_add_u32 v193, v186, 4, v184
	v_lshl_add_u32 v194, v185, 4, v184
	v_lshl_add_u32 v195, v182, 4, v184
	v_lshl_add_u32 v196, v180, 4, v184
	v_lshl_add_u32 v198, v179, 4, v184
	v_lshl_add_u32 v199, v178, 4, v176
	v_lshl_add_u32 v200, v177, 4, v176
	v_readfirstlane_b32 s16, v181
	s_add_i32 s12, s15, -1
	s_lshr_b32 s11, s16, 12
	s_cmp_eq_u32 s11, 0
	s_cbranch_scc1 .Lat3_noprio
	s_setprio 1

.Lat3_epi_b:
	v_mov_b32_e32 v15, v175
	s_nop 1
	v_permlane32_swap_b32_e32 v175, v15
	v_add_f32_e32 v175, v175, v15
	v_div_scale_f32 v2, s[16:17], v175, v175, 1.0
	v_div_scale_f32 v4, vcc, 1.0, v175, 1.0
	v_rcp_f32_e32 v3, v2
	s_nop 1
	v_fma_f32 v5, -v2, v3, 1.0
	v_fmac_f32_e32 v3, v5, v3
	v_mul_f32_e32 v5, v4, v3
	v_fma_f32 v213, -v2, v5, v4
	v_fmac_f32_e32 v5, v213, v3
	v_fma_f32 v2, -v2, v5, v4
	v_div_fmas_f32 v2, v2, v3, v5
	v_div_fixup_f32 v0, v2, v175, 1.0
	s_nop 4
	v_mul_f32_e32 v64, v64, v0
	v_mul_f32_e32 v65, v65, v0
	v_mul_f32_e32 v66, v66, v0
	v_mul_f32_e32 v67, v67, v0
	v_mul_f32_e32 v68, v68, v0
	v_mul_f32_e32 v69, v69, v0
	v_mul_f32_e32 v70, v70, v0
	v_mul_f32_e32 v71, v71, v0
	v_cvt_pk_bf16_f32 v6, v64, v65
	v_cvt_pk_bf16_f32 v7, v66, v67
	v_cvt_pk_bf16_f32 v8, v68, v69
	v_cvt_pk_bf16_f32 v9, v70, v71
	s_nop 1
	s_waitcnt vmcnt(23)
	v_mfma_f32_32x32x16_bf16 v[232:247], v[148:151], v[6:9], 0
	s_waitcnt vmcnt(22)
	v_mfma_f32_32x32x16_bf16 v[80:95], v[144:147], v[6:9], 0
	v_mul_f32_e32 v72, v72, v0
	v_mul_f32_e32 v73, v73, v0
	v_mul_f32_e32 v74, v74, v0
	v_mul_f32_e32 v75, v75, v0
	v_mul_f32_e32 v76, v76, v0
	v_mul_f32_e32 v77, v77, v0
	v_mul_f32_e32 v78, v78, v0
	v_mul_f32_e32 v79, v79, v0
	v_cvt_pk_bf16_f32 v10, v72, v73
	v_cvt_pk_bf16_f32 v11, v74, v75
	v_cvt_pk_bf16_f32 v12, v76, v77
	v_cvt_pk_bf16_f32 v13, v78, v79
	s_nop 1
	s_waitcnt vmcnt(21)
	v_mfma_f32_32x32x16_bf16 v[232:247], v[140:143], v[10:13], v[232:247]
	s_waitcnt vmcnt(20)
	v_mfma_f32_32x32x16_bf16 v[80:95], v[136:139], v[10:13], v[80:95]
	v_mul_f32_e32 v48, v48, v0
	v_mul_f32_e32 v49, v49, v0
	v_mul_f32_e32 v50, v50, v0
	v_mul_f32_e32 v51, v51, v0
	v_mul_f32_e32 v52, v52, v0
	v_mul_f32_e32 v53, v53, v0
	v_mul_f32_e32 v54, v54, v0
	v_mul_f32_e32 v55, v55, v0
	v_cvt_pk_bf16_f32 v6, v48, v49
	v_cvt_pk_bf16_f32 v7, v50, v51
	v_cvt_pk_bf16_f32 v8, v52, v53
	v_cvt_pk_bf16_f32 v9, v54, v55
	s_nop 1
	s_waitcnt vmcnt(19)
	v_mfma_f32_32x32x16_bf16 v[232:247], v[132:135], v[6:9], v[232:247]
	s_waitcnt vmcnt(18)
	v_mfma_f32_32x32x16_bf16 v[80:95], v[128:131], v[6:9], v[80:95]
	v_mul_f32_e32 v56, v56, v0
	v_mul_f32_e32 v57, v57, v0
	v_mul_f32_e32 v58, v58, v0
	v_mul_f32_e32 v59, v59, v0
	v_mul_f32_e32 v60, v60, v0
	v_mul_f32_e32 v61, v61, v0
	v_mul_f32_e32 v62, v62, v0
	v_mul_f32_e32 v63, v63, v0
	v_cvt_pk_bf16_f32 v10, v56, v57
	v_cvt_pk_bf16_f32 v11, v58, v59
	v_cvt_pk_bf16_f32 v12, v60, v61
	v_cvt_pk_bf16_f32 v13, v62, v63
	s_nop 1
	s_waitcnt vmcnt(17)
	v_mfma_f32_32x32x16_bf16 v[232:247], v[124:127], v[10:13], v[232:247]
	s_waitcnt vmcnt(16)
	v_mfma_f32_32x32x16_bf16 v[80:95], v[120:123], v[10:13], v[80:95]
	v_mul_f32_e32 v32, v32, v0
	v_mul_f32_e32 v33, v33, v0
	v_mul_f32_e32 v34, v34, v0
	v_mul_f32_e32 v35, v35, v0
	v_mul_f32_e32 v36, v36, v0
	v_mul_f32_e32 v37, v37, v0
	v_mul_f32_e32 v38, v38, v0
	v_mul_f32_e32 v39, v39, v0
	v_cvt_pk_bf16_f32 v6, v32, v33
	v_cvt_pk_bf16_f32 v7, v34, v35
	v_cvt_pk_bf16_f32 v8, v36, v37
	v_cvt_pk_bf16_f32 v9, v38, v39
	s_nop 1
	s_waitcnt vmcnt(15)
	v_mfma_f32_32x32x16_bf16 v[232:247], v[116:119], v[6:9], v[232:247]
	s_waitcnt vmcnt(14)
	v_mfma_f32_32x32x16_bf16 v[80:95], v[112:115], v[6:9], v[80:95]
	v_mul_f32_e32 v40, v40, v0
	v_mul_f32_e32 v41, v41, v0
	v_mul_f32_e32 v42, v42, v0
	v_mul_f32_e32 v43, v43, v0
	v_mul_f32_e32 v44, v44, v0
	v_mul_f32_e32 v45, v45, v0
	v_mul_f32_e32 v46, v46, v0
	v_mul_f32_e32 v47, v47, v0
	v_cvt_pk_bf16_f32 v10, v40, v41
	v_cvt_pk_bf16_f32 v11, v42, v43
	v_cvt_pk_bf16_f32 v12, v44, v45
	v_cvt_pk_bf16_f32 v13, v46, v47
	s_nop 1
	s_waitcnt vmcnt(13)
	v_mfma_f32_32x32x16_bf16 v[232:247], v[220:223], v[10:13], v[232:247]
	s_waitcnt vmcnt(12)
	v_mfma_f32_32x32x16_bf16 v[80:95], v[224:227], v[10:13], v[80:95]
	v_mul_f32_e32 v16, v16, v0
	v_mul_f32_e32 v17, v17, v0
	v_mul_f32_e32 v18, v18, v0
	v_mul_f32_e32 v19, v19, v0
	v_mul_f32_e32 v20, v20, v0
	v_mul_f32_e32 v21, v21, v0
	v_mul_f32_e32 v22, v22, v0
	v_mul_f32_e32 v23, v23, v0
	v_cvt_pk_bf16_f32 v6, v16, v17
	v_cvt_pk_bf16_f32 v7, v18, v19
	v_cvt_pk_bf16_f32 v8, v20, v21
	v_cvt_pk_bf16_f32 v9, v22, v23
	s_nop 1
	s_waitcnt vmcnt(11)
	v_mfma_f32_32x32x16_bf16 v[232:247], v[228:231], v[6:9], v[232:247]
	s_waitcnt vmcnt(10)
	v_mfma_f32_32x32x16_bf16 v[80:95], v[96:99], v[6:9], v[80:95]
	v_mul_f32_e32 v24, v24, v0
	v_mul_f32_e32 v25, v25, v0
	v_mul_f32_e32 v26, v26, v0
	v_mul_f32_e32 v27, v27, v0
	v_mul_f32_e32 v28, v28, v0
	v_mul_f32_e32 v29, v29, v0
	v_mul_f32_e32 v30, v30, v0
	v_mul_f32_e32 v31, v31, v0
	v_cvt_pk_bf16_f32 v10, v24, v25
	v_cvt_pk_bf16_f32 v11, v26, v27
	v_cvt_pk_bf16_f32 v12, v28, v29
	v_cvt_pk_bf16_f32 v13, v30, v31
	s_nop 1
	s_waitcnt vmcnt(9)
	v_mfma_f32_32x32x16_bf16 v[232:247], v[100:103], v[10:13], v[232:247]
	s_waitcnt vmcnt(8)
	v_mfma_f32_32x32x16_bf16 v[80:95], v[104:107], v[10:13], v[80:95]
	v_cmp_gt_u32_e32 vcc, s76, v167
	s_and_saveexec_b64 s[6:7], vcc
	s_cbranch_execz .LBB0_470
	s_nop 10
	s_waitcnt vmcnt(7)
	v_lshlrev_b32_e32 v2, 16, v190
	v_and_b32_e32 v3, 0xffff0000, v190
	v_lshlrev_b32_e32 v4, 16, v191
	v_and_b32_e32 v5, 0xffff0000, v191
	v_mul_f32_e32 v232, v232, v2
	v_mul_f32_e32 v233, v233, v3
	v_mul_f32_e32 v234, v234, v4
	v_mul_f32_e32 v235, v235, v5
	v_cvt_pk_bf16_f32 v190, v232, v233
	v_cvt_pk_bf16_f32 v191, v234, v235
	s_waitcnt vmcnt(6)
	v_lshlrev_b32_e32 v2, 16, v192
	v_and_b32_e32 v3, 0xffff0000, v192
	v_lshlrev_b32_e32 v4, 16, v193
	v_and_b32_e32 v5, 0xffff0000, v193
	v_mul_f32_e32 v236, v236, v2
	v_mul_f32_e32 v237, v237, v3
	v_mul_f32_e32 v238, v238, v4
	v_mul_f32_e32 v239, v239, v5
	v_cvt_pk_bf16_f32 v192, v236, v237
	v_cvt_pk_bf16_f32 v193, v238, v239
	s_waitcnt vmcnt(5)
	v_lshlrev_b32_e32 v2, 16, v194
	v_and_b32_e32 v3, 0xffff0000, v194
	v_lshlrev_b32_e32 v4, 16, v195
	v_and_b32_e32 v5, 0xffff0000, v195
	v_mul_f32_e32 v240, v240, v2
	v_mul_f32_e32 v241, v241, v3
	v_mul_f32_e32 v242, v242, v4
	v_mul_f32_e32 v243, v243, v5
	v_cvt_pk_bf16_f32 v194, v240, v241
	v_cvt_pk_bf16_f32 v195, v242, v243
	s_waitcnt vmcnt(4)
	v_lshlrev_b32_e32 v2, 16, v198
	v_and_b32_e32 v3, 0xffff0000, v198
	v_lshlrev_b32_e32 v4, 16, v199
	v_and_b32_e32 v5, 0xffff0000, v199
	v_mul_f32_e32 v244, v244, v2
	v_mul_f32_e32 v245, v245, v3
	v_mul_f32_e32 v246, v246, v4
	v_mul_f32_e32 v247, v247, v5
	v_cvt_pk_bf16_f32 v198, v244, v245
	v_cvt_pk_bf16_f32 v199, v246, v247
	s_waitcnt vmcnt(3)
	v_lshlrev_b32_e32 v2, 16, v200
	v_and_b32_e32 v3, 0xffff0000, v200
	v_lshlrev_b32_e32 v4, 16, v201
	v_and_b32_e32 v5, 0xffff0000, v201
	v_mul_f32_e32 v80, v80, v2
	v_mul_f32_e32 v81, v81, v3
	v_mul_f32_e32 v82, v82, v4
	v_mul_f32_e32 v83, v83, v5
	v_cvt_pk_bf16_f32 v200, v80, v81
	v_cvt_pk_bf16_f32 v201, v82, v83
	s_waitcnt vmcnt(2)
	v_lshlrev_b32_e32 v2, 16, v202
	v_and_b32_e32 v3, 0xffff0000, v202
	v_lshlrev_b32_e32 v4, 16, v203
	v_and_b32_e32 v5, 0xffff0000, v203
	v_mul_f32_e32 v84, v84, v2
	v_mul_f32_e32 v85, v85, v3
	v_mul_f32_e32 v86, v86, v4
	v_mul_f32_e32 v87, v87, v5
	v_cvt_pk_bf16_f32 v202, v84, v85
	v_cvt_pk_bf16_f32 v203, v86, v87
	s_waitcnt vmcnt(1)
	v_lshlrev_b32_e32 v2, 16, v216
	v_and_b32_e32 v3, 0xffff0000, v216
	v_lshlrev_b32_e32 v4, 16, v217
	v_and_b32_e32 v5, 0xffff0000, v217
	v_mul_f32_e32 v88, v88, v2
	v_mul_f32_e32 v89, v89, v3
	v_mul_f32_e32 v90, v90, v4
	v_mul_f32_e32 v91, v91, v5
	v_cvt_pk_bf16_f32 v216, v88, v89
	v_cvt_pk_bf16_f32 v217, v90, v91
	s_waitcnt vmcnt(0)
	v_lshlrev_b32_e32 v2, 16, v248
	v_and_b32_e32 v3, 0xffff0000, v248
	v_lshlrev_b32_e32 v4, 16, v249
	v_and_b32_e32 v5, 0xffff0000, v249
	v_mul_f32_e32 v92, v92, v2
	v_mul_f32_e32 v93, v93, v3
	v_mul_f32_e32 v94, v94, v4
	v_mul_f32_e32 v95, v95, v5
	v_cvt_pk_bf16_f32 v248, v92, v93
	v_cvt_pk_bf16_f32 v249, v94, v95
	global_store_dwordx2 v212, v[190:191], s[52:53] offset:0 sc0 sc1
	global_store_dwordx2 v212, v[192:193], s[52:53] offset:16 sc0 sc1
	global_store_dwordx2 v212, v[194:195], s[52:53] offset:32 sc0 sc1
	global_store_dwordx2 v212, v[198:199], s[52:53] offset:48 sc0 sc1
	global_store_dwordx2 v212, v[200:201], s[52:53] offset:64 sc0 sc1
	global_store_dwordx2 v212, v[202:203], s[52:53] offset:80 sc0 sc1
	global_store_dwordx2 v212, v[216:217], s[52:53] offset:96 sc0 sc1
	global_store_dwordx2 v212, v[248:249], s[52:53] offset:112 sc0 sc1
	s_mov_b32 s96, s97
	s_branch .LBB0_470

.Le4a_call:
	s_cmp_eq_u32 s96, 0
	s_cbranch_scc1 .Lrel_none_e
	s_waitcnt vmcnt(0)
	s_barrier
	s_and_saveexec_b64 s[18:19], s[80:81]
	s_cbranch_execz .Lrel_done_e
	v_mov_b32_e32 v2, s96
	v_mov_b32_e32 v3, 1
	global_atomic_add v2, v3, s[78:79]

.Lrel_none_x:
	s_mov_b64 s[6:7], 0
	s_branch .Lq_done

.LBB0_504:
	s_waitcnt vmcnt(0)
	s_barrier
	s_and_saveexec_b64 s[2:3], s[80:81]
	s_cbranch_execz .LBB0_521
	s_lshl_b32 s4, s91, 2
	s_addk_i32 s4, 0x3c00
	v_mov_b32_e32 v0, s4
.Lm4_poll:
	global_load_dword v1, v0, s[78:79] sc1
	s_waitcnt vmcnt(0)
	v_cmp_gt_u32_e32 vcc, 8, v1
	s_cbranch_vccz .Lm4_done
	s_sleep 1
	s_branch .Lm4_poll
.Lm4_done:
	buffer_inv sc1
	s_waitcnt vmcnt(0)

.Le4a_entry:
	v_mov_b32_e32 v0, v218
	s_barrier
	s_add_u32 s6, s38, 0xa8a8000
	v_ashrrev_i32_e32 v2, 2, v0
	v_bfe_u32 v3, v0, 4, 2
	v_lshlrev_b32_e32 v4, 3, v0
	v_lshrrev_b32_e32 v5, 5, v2
	s_mov_b32 s2, 0x8200
	s_addc_u32 s7, s39, 0
	v_lshlrev_b32_e32 v1, 1, v0
	v_and_b32_e32 v196, 0x78, v4
	v_mul_lo_u32 v5, v5, s2
	v_mul_u32_u24_e32 v6, 0x410, v3
	v_and_b32_e32 v4, 0x200, v4
	v_and_b32_e32 v0, 15, v0
	s_movk_i32 s2, 0xffe0
	s_add_u32 s8, s38, 0xc928000
	v_add3_u32 v4, v5, v6, v4
	v_lshlrev_b32_e32 v0, 5, v0
	v_and_or_b32 v222, v2, s2, v3
	s_addc_u32 s9, s39, 0
	v_and_b32_e32 v220, 0x80, v1
	s_add_i32 s4, s86, 0xffffff04
	s_cmp_lg_u32 s101, 1
	s_cbranch_scc1 .Le4a_regular
	s_add_i32 s4, s100, 0xffffff00
.Le4a_regular:
	v_mov_b32_e32 v1, 0
	s_and_b32 s5, s101, 1
	v_add3_u32 v221, v4, v0, 0
	v_add_u32_e32 v223, 0x84, v222
	s_mov_b32 s40, 0x77e8000
	s_mov_b32 s41, 0x53c0000
	s_movk_i32 s52, 0x3000
	s_mov_b64 s[10:11], 0x80
	s_mov_b64 s[12:13], 0x20080
	s_mov_b64 s[14:15], 0x100
	s_mov_b64 s[16:17], 0x20100
	s_mov_b64 s[18:19], 0x180
	s_mov_b64 s[20:21], 0x20180
	s_mov_b64 s[22:23], 0x380
	s_movk_i32 s53, 0x100
	v_mov_b32_e32 v224, 1
	s_branch .LBB0_524

.LBB0_569:
	s_or_b64 exec, exec, s[10:11]
	s_waitcnt vmcnt(0)
	v_readfirstlane_b32 s4, v1
	s_nop 1
	v_add_u32_e32 v0, s4, v0
	s_lshl_b32 s4, s84, 2
	s_add_i32 s4, s4, -1
	v_cmp_ne_u32_e32 vcc, s4, v0
	s_and_saveexec_b64 s[4:5], vcc
	s_xor_b64 s[8:9], exec, s[4:5]
	s_cbranch_execz .LBB0_573
	v_mov_b32_e32 v0, 0x2000
	global_load_dword v0, v0, s[6:7] sc1
	s_add_u32 s10, s6, 0x2000
	s_addc_u32 s11, s7, 0
	s_waitcnt vmcnt(0)
	v_cmp_lt_u32_e32 vcc, 4, v0
	s_cbranch_vccnz .LBB0_573
	v_mov_b32_e32 v0, 0
